# P6 epilogue x loads marked non-temporal (last use of x): stream no longer displaces x_new / converted weights
# speedup vs baseline: 1.0152x; 1.0152x over previous
.LBB0_1317:
	v_readlane_b32 s12, v252, 42
	v_readlane_b32 s26, v252, 56
	v_readlane_b32 s27, v252, 57
	s_add_u32 s6, s26, 0x1bc00000
	s_addc_u32 s7, s27, 0
	s_ashr_i32 s9, s8, 3
	v_lshl_or_b32 v114, s9, 4, v179
	v_ashrrev_i32_e32 v115, 31, v114
	s_lshl_b32 s10, s4, 8
	v_readlane_b32 s13, v252, 43
	v_lshlrev_b64 v[114:115], 12, v[114:115]
	s_ashr_i32 s11, s10, 31
	v_readlane_b32 s14, v252, 44
	v_readlane_b32 s15, v252, 45
	v_lshl_add_u64 v[114:115], s[26:27], 0, v[114:115]
	s_lshl_b64 s[12:13], s[10:11], 2
	v_lshl_add_u64 v[114:115], v[114:115], 0, s[12:13]
	s_lshl_b32 s14, s33, 7
	s_mov_b32 s15, 0
	v_lshl_add_u64 v[114:115], v[114:115], 0, s[14:15]
	v_lshlrev_b32_e32 v146, 5, v181
	v_mov_b32_e32 v147, 0
	v_lshl_add_u64 v[114:115], v[114:115], 0, v[146:147]
	s_mov_b32 s11, 0x7500000
	s_mov_b64 s[0:1], 0x7500000
	v_add_co_u32_e32 v116, vcc, s11, v114
	s_waitcnt vmcnt(0)
	s_barrier
	s_nop 0
	v_addc_co_u32_e32 v117, vcc, 0, v115, vcc
	v_lshl_add_u64 v[114:115], v[114:115], 0, s[0:1]
	s_mul_hi_i32 s0, s9, 0x6000
	s_mulk_i32 s9, 0x6000
	s_add_u32 s1, s26, s9
	s_addc_u32 s0, s27, s0
	global_load_dwordx4 v[130:133], v[116:117], off
	s_add_u32 s1, s1, s12
	s_addc_u32 s9, s0, s13
	s_add_u32 s0, s1, s14
	s_addc_u32 s1, s9, 0
	global_load_dwordx4 v[134:137], v[114:115], off offset:16
	global_load_dwordx4 v[188:191], v[114:115], off offset:528
	global_load_dwordx4 v[192:195], v[114:115], off offset:512
	v_lshl_add_u64 v[114:115], s[0:1], 0, v[146:147]
	s_mov_b64 s[0:1], 0x102000
	v_lshl_add_u64 v[122:123], v[114:115], 0, s[0:1]
	s_mov_b32 s0, 0x102000
	v_add_co_u32_e32 v114, vcc, s0, v114
	s_lshl_b32 s0, s8, 8
	v_readlane_b32 s16, v252, 46
	v_readlane_b32 s17, v252, 47
	v_readlane_b32 s18, v252, 48
	v_readlane_b32 s19, v252, 49
	v_readlane_b32 s20, v252, 50
	v_readlane_b32 s21, v252, 51
	v_readlane_b32 s22, v252, 52
	v_readlane_b32 s23, v252, 53
	v_readlane_b32 s24, v252, 54
	v_readlane_b32 s25, v252, 55
	s_add_i32 s1, s0, s5
	v_or_b32_e32 v184, s1, v179
	s_lshl_b32 s1, s33, 10
	v_readlane_b32 s16, v252, 58
	s_add_i32 s1, s1, 0
	v_readlane_b32 s17, v252, 59
	s_add_i32 s1, s1, 0x10000
	s_mov_b64 s[8:9], s[16:17]
	s_add_u32 s8, s8, s12
	s_addc_u32 s9, s9, s13
	s_add_u32 s8, s8, s14
	s_addc_u32 s9, s9, 0
	v_ashrrev_i32_e32 v185, 31, v184
	v_lshl_add_u64 v[186:187], s[8:9], 0, v[146:147]
	v_lshlrev_b64 v[146:147], 12, v[184:185]
	v_addc_co_u32_e32 v115, vcc, 0, v115, vcc
	v_lshl_add_u64 v[146:147], v[186:187], 0, v[146:147]
	global_load_dwordx4 v[142:145], v[114:115], off
	s_nop 0
	global_load_dwordx4 v[114:117], v[122:123], off offset:528
	global_load_dwordx4 v[138:141], v[122:123], off offset:16
	s_nop 0
	global_load_dwordx4 v[122:125], v[122:123], off offset:512
	s_nop 0
	global_load_dwordx4 v[196:199], v[146:147], off offset:16 nt
	global_load_dwordx4 v[200:203], v[146:147], off nt
	global_load_dwordx4 v[204:207], v[146:147], off offset:528 nt
	global_load_dwordx4 v[208:211], v[146:147], off offset:512 nt
	v_or_b32_e32 v146, 16, v184
	v_ashrrev_i32_e32 v147, 31, v146
	v_lshlrev_b64 v[146:147], 12, v[146:147]
	v_lshl_add_u64 v[146:147], v[186:187], 0, v[146:147]
	global_load_dwordx4 v[170:173], v[146:147], off offset:16 nt
	global_load_dwordx4 v[174:177], v[146:147], off nt
	global_load_dwordx4 v[162:165], v[146:147], off offset:528 nt
	global_load_dwordx4 v[166:169], v[146:147], off offset:512 nt
	v_lshlrev_b32_e32 v185, 3, v181
	v_readlane_b32 s18, v252, 60
	v_readlane_b32 s19, v252, 61
	v_readlane_b32 s20, v252, 62
	v_readlane_b32 s21, v252, 63
	v_readlane_b32 s22, v251, 0
	v_readlane_b32 s23, v251, 1
	v_readlane_b32 s24, v251, 2
	v_readlane_b32 s25, v251, 3
	v_readlane_b32 s26, v251, 4
	v_readlane_b32 s27, v251, 5
	v_readlane_b32 s28, v251, 6
	v_readlane_b32 s29, v251, 7
	v_readlane_b32 s30, v251, 8
	v_readlane_b32 s31, v251, 9
	v_lshl_add_u32 v216, v179, 2, s1
	s_waitcnt vmcnt(0)
	v_cvt_pk_bf16_f32 v146, v130, v131
	v_lshlrev_b32_e32 v154, 16, v146
	v_and_b32_e32 v155, 0xffff0000, v146
	v_pk_add_f32 v[130:131], v[130:131], v[154:155] neg_lo:[0,1] neg_hi:[0,1]
	v_cvt_pk_bf16_f32 v149, v136, v137
	v_cvt_pk_bf16_f32 v147, v132, v133
	v_cvt_pk_bf16_f32 v154, v130, v131
	v_lshlrev_b32_e32 v130, 16, v149
	v_and_b32_e32 v131, 0xffff0000, v149
	v_lshlrev_b32_e32 v156, 16, v147
	v_and_b32_e32 v157, 0xffff0000, v147
	v_pk_add_f32 v[130:131], v[136:137], v[130:131] neg_lo:[0,1] neg_hi:[0,1]
	v_cvt_pk_bf16_f32 v148, v134, v135
	v_pk_add_f32 v[132:133], v[132:133], v[156:157] neg_lo:[0,1] neg_hi:[0,1]
	v_cvt_pk_bf16_f32 v157, v130, v131
	v_cvt_pk_bf16_f32 v130, v192, v193
	v_lshlrev_b32_e32 v182, 16, v148
	v_and_b32_e32 v183, 0xffff0000, v148
	v_cvt_pk_bf16_f32 v155, v132, v133
	v_lshlrev_b32_e32 v132, 16, v130
	v_and_b32_e32 v133, 0xffff0000, v130
	v_pk_add_f32 v[134:135], v[134:135], v[182:183] neg_lo:[0,1] neg_hi:[0,1]
	v_pk_add_f32 v[132:133], v[192:193], v[132:133] neg_lo:[0,1] neg_hi:[0,1]
	v_cvt_pk_bf16_f32 v131, v194, v195
	v_cvt_pk_bf16_f32 v156, v134, v135
	v_cvt_pk_bf16_f32 v134, v132, v133
	v_lshlrev_b32_e32 v132, 16, v131
	v_and_b32_e32 v133, 0xffff0000, v131
	v_pk_add_f32 v[132:133], v[194:195], v[132:133] neg_lo:[0,1] neg_hi:[0,1]
	s_nop 0
	v_cvt_pk_bf16_f32 v135, v132, v133
	v_cvt_pk_bf16_f32 v132, v188, v189
	v_cvt_pk_bf16_f32 v133, v190, v191
	v_lshlrev_b32_e32 v136, 16, v132
	v_and_b32_e32 v137, 0xffff0000, v132
	v_lshlrev_b32_e32 v182, 16, v133
	v_and_b32_e32 v183, 0xffff0000, v133
	v_pk_add_f32 v[136:137], v[188:189], v[136:137] neg_lo:[0,1] neg_hi:[0,1]
	v_pk_add_f32 v[182:183], v[190:191], v[182:183] neg_lo:[0,1] neg_hi:[0,1]
	v_cvt_pk_bf16_f32 v136, v136, v137
	v_cvt_pk_bf16_f32 v137, v182, v183
	v_mbcnt_lo_u32_b32 v183, -1, 0
	v_mbcnt_hi_u32_b32 v183, -1, v183
	v_and_b32_e32 v188, 64, v183
	v_lshl_or_b32 v182, s33, 5, v185
	v_xor_b32_e32 v185, 16, v183
	v_add_u32_e32 v190, 64, v188
	v_cmp_lt_i32_e32 vcc, v185, v190
	v_or_b32_e32 v189, s0, v179
	v_or_b32_e32 v182, s10, v182
	v_cndmask_b32_e32 v185, v183, v185, vcc
	v_lshlrev_b32_e32 v188, 2, v185
	v_xor_b32_e32 v185, 32, v183
	v_cmp_lt_i32_e32 vcc, v185, v190
	s_nop 1
	v_cndmask_b32_e32 v183, v183, v185, vcc
	v_lshlrev_b32_e32 v185, 2, v183
	v_cmp_eq_u32_e32 vcc, 0, v181
	v_add_u32_e32 v190, s5, v189
	v_ashrrev_i32_e32 v191, 31, v190
	v_lshlrev_b64 v[194:195], 11, v[190:191]
	v_pk_fma_f32 v[190:191], v[158:159], v[142:143], v[200:201]
	v_pk_fma_f32 v[160:161], v[160:161], v[144:145], v[202:203]
	v_cvt_pk_bf16_f32 v158, v190, v191
	v_lshlrev_b32_e32 v192, 16, v158
	v_and_b32_e32 v193, 0xffff0000, v158
	v_cvt_pk_bf16_f32 v159, v160, v161
	v_pk_mul_f32 v[202:203], v[190:191], v[190:191]
	v_pk_add_f32 v[190:191], v[190:191], v[192:193] neg_lo:[0,1] neg_hi:[0,1]
	v_lshlrev_b32_e32 v192, 16, v159
	v_and_b32_e32 v193, 0xffff0000, v159
	v_pk_mul_f32 v[200:201], v[160:161], v[160:161]
	v_pk_add_f32 v[160:161], v[160:161], v[192:193] neg_lo:[0,1] neg_hi:[0,1]
	v_pk_fma_f32 v[198:199], v[152:153], v[140:141], v[198:199]
	v_pk_fma_f32 v[150:151], v[150:151], v[138:139], v[196:197]
	v_cvt_pk_bf16_f32 v190, v190, v191
	v_cvt_pk_bf16_f32 v191, v160, v161
	v_cvt_pk_bf16_f32 v160, v150, v151
	v_cvt_pk_bf16_f32 v161, v198, v199
	v_lshlrev_b32_e32 v152, 16, v160
	v_and_b32_e32 v153, 0xffff0000, v160
	v_pk_mul_f32 v[212:213], v[150:151], v[150:151]
	v_pk_add_f32 v[150:151], v[150:151], v[152:153] neg_lo:[0,1] neg_hi:[0,1]
	v_lshlrev_b32_e32 v214, 16, v161
	v_cvt_pk_bf16_f32 v192, v150, v151
	v_mfma_f32_16x16x32_bf16 v[150:153], v[158:161], v[146:149], 0
	v_and_b32_e32 v215, 0xffff0000, v161
	v_pk_mul_f32 v[196:197], v[198:199], v[198:199]
	v_pk_add_f32 v[198:199], v[198:199], v[214:215] neg_lo:[0,1] neg_hi:[0,1]
	v_lshl_add_u64 v[194:195], s[6:7], 0, v[194:195]
	v_cvt_pk_bf16_f32 v193, v198, v199
	v_ashrrev_i32_e32 v183, 31, v182
	v_mfma_f32_16x16x32_bf16 v[150:153], v[158:161], v[154:157], v[150:153]
	v_lshl_add_u64 v[194:195], v[182:183], 1, v[194:195]
	global_store_dwordx4 v[194:195], v[158:161], off
	v_pk_fma_f32 v[128:129], v[128:129], v[124:125], v[210:211]
	v_mfma_f32_16x16x32_bf16 v[150:153], v[190:193], v[146:149], v[150:153]
	v_fma_f32 v158, v126, v122, v208
	v_fma_f32 v159, v127, v123, v209
	v_cvt_pk_bf16_f32 v127, v128, v129
	v_cvt_pk_bf16_f32 v126, v158, v159
	v_lshlrev_b32_e32 v160, 16, v126
	v_and_b32_e32 v161, 0xffff0000, v126
	v_pk_mul_f32 v[192:193], v[158:159], v[158:159]
	v_pk_add_f32 v[158:159], v[158:159], v[160:161] neg_lo:[0,1] neg_hi:[0,1]
	v_lshlrev_b32_e32 v160, 16, v127
	v_and_b32_e32 v161, 0xffff0000, v127
	v_pk_mul_f32 v[190:191], v[128:129], v[128:129]
	v_pk_add_f32 v[128:129], v[128:129], v[160:161] neg_lo:[0,1] neg_hi:[0,1]
	v_pk_fma_f32 v[118:119], v[118:119], v[114:115], v[204:205]
	v_cvt_pk_bf16_f32 v158, v158, v159
	v_cvt_pk_bf16_f32 v159, v128, v129
	v_cvt_pk_bf16_f32 v128, v118, v119
	v_pk_fma_f32 v[198:199], v[120:121], v[116:117], v[206:207]
	v_lshlrev_b32_e32 v160, 16, v128
	v_and_b32_e32 v161, 0xffff0000, v128
	v_pk_mul_f32 v[120:121], v[198:199], v[198:199]
	v_pk_mul_f32 v[204:205], v[118:119], v[118:119]
	v_pk_add_f32 v[118:119], v[118:119], v[160:161] neg_lo:[0,1] neg_hi:[0,1]
	v_cvt_pk_bf16_f32 v129, v198, v199
	v_cvt_pk_bf16_f32 v160, v118, v119
	v_add_f32_e32 v118, v120, v121
	v_add_f32_e32 v119, v204, v205
	v_add_f32_e32 v118, v119, v118
	v_add_f32_e32 v119, v190, v191
	v_add_f32_e32 v120, v192, v193
	v_add_f32_e32 v119, v120, v119
	v_add_f32_e32 v118, v119, v118
	v_add_f32_e32 v119, v196, v197
	v_add_f32_e32 v120, v212, v213
	v_add_f32_e32 v119, v120, v119
	v_add_f32_e32 v120, v200, v201
	v_add_f32_e32 v121, v202, v203
	v_add_f32_e32 v120, v121, v120
	v_add_f32_e32 v119, v120, v119
	v_add_f32_e32 v190, v119, v118
	v_mfma_f32_16x16x32_bf16 v[118:121], v[126:129], v[130:133], v[150:153]
	v_lshlrev_b32_e32 v206, 16, v129
	v_and_b32_e32 v207, 0xffff0000, v129
	global_store_dwordx4 v[194:195], v[126:129], off offset:256
	ds_bpermute_b32 v152, v188, v190
	v_pk_add_f32 v[150:151], v[198:199], v[206:207] neg_lo:[0,1] neg_hi:[0,1]
	v_mfma_f32_16x16x32_bf16 v[118:121], v[126:129], v[134:137], v[118:121]
	v_cvt_pk_bf16_f32 v161, v150, v151
	v_lshl_add_u32 v126, s5, 2, v216
	s_waitcnt lgkmcnt(0)
	v_add_f32_e32 v127, v190, v152
	ds_bpermute_b32 v128, v185, v127
	v_mfma_f32_16x16x32_bf16 v[118:121], v[158:161], v[130:133], v[118:121]
	s_and_saveexec_b64 s[8:9], vcc
	s_cbranch_execz .LBB0_1319
	s_waitcnt lgkmcnt(0)
	v_add_f32_e32 v127, v127, v128
	ds_write_b32 v126, v127

.LBB0_1321:
	s_or_b64 exec, exec, s[8:9]
	v_add_u32_e32 v102, s1, v127
	v_lshl_add_u32 v102, v102, 6, v128
	s_nop 2
	ds_write2_b32 v102, v98, v99 offset1:16
	ds_write2_b32 v102, v100, v101 offset0:32 offset1:48
	v_or_b32_e32 v98, 32, v184
	v_ashrrev_i32_e32 v99, 31, v98
	v_lshlrev_b64 v[98:99], 12, v[98:99]
	v_lshl_add_u64 v[98:99], v[186:187], 0, v[98:99]
	global_load_dwordx4 v[118:121], v[98:99], off offset:16 nt
	global_load_dwordx4 v[150:153], v[98:99], off nt
	global_load_dwordx4 v[158:161], v[98:99], off offset:528 nt
	global_load_dwordx4 v[162:165], v[98:99], off offset:512 nt
	v_or_b32_e32 v98, 48, v184
	v_ashrrev_i32_e32 v99, 31, v98
	v_lshlrev_b64 v[98:99], 12, v[98:99]
	s_waitcnt lgkmcnt(2)
	v_lshl_add_u64 v[102:103], v[186:187], 0, v[98:99]
	global_load_dwordx4 v[106:109], v[102:103], off offset:16 nt
	global_load_dwordx4 v[110:113], v[102:103], off nt
	global_load_dwordx4 v[98:101], v[102:103], off offset:528 nt
	s_nop 0
	global_load_dwordx4 v[102:105], v[102:103], off offset:512 nt
	s_waitcnt vmcnt(6)
	v_pk_fma_f32 v[150:151], v[94:95], v[142:143], v[150:151]
	v_pk_fma_f32 v[96:97], v[96:97], v[144:145], v[152:153]
	v_cvt_pk_bf16_f32 v94, v150, v151
	v_lshlrev_b32_e32 v152, 16, v94
	v_and_b32_e32 v153, 0xffff0000, v94
	v_cvt_pk_bf16_f32 v95, v96, v97
	v_pk_mul_f32 v[170:171], v[150:151], v[150:151]
	v_pk_add_f32 v[150:151], v[150:151], v[152:153] neg_lo:[0,1] neg_hi:[0,1]
	v_lshlrev_b32_e32 v152, 16, v95
	v_and_b32_e32 v153, 0xffff0000, v95
	v_pk_mul_f32 v[168:169], v[96:97], v[96:97]
	v_pk_add_f32 v[96:97], v[96:97], v[152:153] neg_lo:[0,1] neg_hi:[0,1]
	v_pk_fma_f32 v[120:121], v[92:93], v[140:141], v[120:121]
	v_pk_fma_f32 v[90:91], v[90:91], v[138:139], v[118:119]
	v_cvt_pk_bf16_f32 v150, v150, v151
	v_cvt_pk_bf16_f32 v151, v96, v97
	v_cvt_pk_bf16_f32 v96, v90, v91
	v_cvt_pk_bf16_f32 v97, v120, v121
	v_lshlrev_b32_e32 v92, 16, v96
	v_and_b32_e32 v93, 0xffff0000, v96
	s_or_b32 s1, s5, 32
	v_pk_mul_f32 v[172:173], v[90:91], v[90:91]
	v_pk_add_f32 v[90:91], v[90:91], v[92:93] neg_lo:[0,1] neg_hi:[0,1]
	v_add_u32_e32 v166, s1, v189
	v_cvt_pk_bf16_f32 v152, v90, v91
	v_mfma_f32_16x16x32_bf16 v[90:93], v[94:97], v[146:149], 0
	v_ashrrev_i32_e32 v167, 31, v166
	v_lshlrev_b32_e32 v174, 16, v97
	v_and_b32_e32 v175, 0xffff0000, v97
	v_lshlrev_b64 v[166:167], 11, v[166:167]
	v_pk_mul_f32 v[118:119], v[120:121], v[120:121]
	v_pk_add_f32 v[120:121], v[120:121], v[174:175] neg_lo:[0,1] neg_hi:[0,1]
	v_mfma_f32_16x16x32_bf16 v[90:93], v[94:97], v[154:157], v[90:93]
	v_cvt_pk_bf16_f32 v153, v120, v121
	v_lshl_add_u64 v[120:121], s[6:7], 0, v[166:167]
	v_lshl_add_u64 v[120:121], v[182:183], 1, v[120:121]
	global_store_dwordx4 v[120:121], v[94:97], off
	s_waitcnt vmcnt(5)
	v_pk_fma_f32 v[88:89], v[88:89], v[124:125], v[164:165]
	v_mfma_f32_16x16x32_bf16 v[90:93], v[150:153], v[146:149], v[90:93]
	v_fma_f32 v94, v86, v122, v162
	v_fma_f32 v95, v87, v123, v163
	v_cvt_pk_bf16_f32 v87, v88, v89
	v_cvt_pk_bf16_f32 v86, v94, v95
	v_lshlrev_b32_e32 v96, 16, v86
	v_and_b32_e32 v97, 0xffff0000, v86
	v_pk_mul_f32 v[152:153], v[94:95], v[94:95]
	v_pk_add_f32 v[94:95], v[94:95], v[96:97] neg_lo:[0,1] neg_hi:[0,1]
	v_lshlrev_b32_e32 v96, 16, v87
	v_and_b32_e32 v97, 0xffff0000, v87
	v_pk_mul_f32 v[150:151], v[88:89], v[88:89]
	v_pk_add_f32 v[88:89], v[88:89], v[96:97] neg_lo:[0,1] neg_hi:[0,1]
	v_pk_fma_f32 v[82:83], v[82:83], v[114:115], v[158:159]
	v_cvt_pk_bf16_f32 v94, v94, v95
	v_cvt_pk_bf16_f32 v95, v88, v89
	v_cvt_pk_bf16_f32 v88, v82, v83
	v_pk_fma_f32 v[160:161], v[84:85], v[116:117], v[160:161]
	v_lshlrev_b32_e32 v96, 16, v88
	v_and_b32_e32 v97, 0xffff0000, v88
	v_pk_mul_f32 v[84:85], v[160:161], v[160:161]
	v_pk_mul_f32 v[158:159], v[82:83], v[82:83]
	v_pk_add_f32 v[82:83], v[82:83], v[96:97] neg_lo:[0,1] neg_hi:[0,1]
	v_cvt_pk_bf16_f32 v89, v160, v161
	v_cvt_pk_bf16_f32 v96, v82, v83
	v_add_f32_e32 v82, v84, v85
	v_add_f32_e32 v83, v158, v159
	v_add_f32_e32 v82, v83, v82
	v_add_f32_e32 v83, v150, v151
	v_add_f32_e32 v84, v152, v153
	v_add_f32_e32 v83, v84, v83
	v_add_f32_e32 v82, v83, v82
	v_add_f32_e32 v83, v118, v119
	v_add_f32_e32 v84, v172, v173
	v_add_f32_e32 v83, v84, v83
	v_add_f32_e32 v84, v168, v169
	v_add_f32_e32 v85, v170, v171
	v_add_f32_e32 v84, v85, v84
	v_add_f32_e32 v83, v84, v83
	v_add_f32_e32 v118, v83, v82
	v_mfma_f32_16x16x32_bf16 v[82:85], v[86:89], v[130:133], v[90:93]
	v_lshlrev_b32_e32 v162, 16, v89
	v_and_b32_e32 v163, 0xffff0000, v89
	global_store_dwordx4 v[120:121], v[86:89], off offset:256
	ds_bpermute_b32 v92, v188, v118
	v_pk_add_f32 v[90:91], v[160:161], v[162:163] neg_lo:[0,1] neg_hi:[0,1]
	v_mfma_f32_16x16x32_bf16 v[82:85], v[86:89], v[134:137], v[82:85]
	v_cvt_pk_bf16_f32 v97, v90, v91
	s_waitcnt lgkmcnt(0)
	v_add_f32_e32 v86, v118, v92
	ds_bpermute_b32 v87, v185, v86
	v_mfma_f32_16x16x32_bf16 v[82:85], v[94:97], v[130:133], v[82:85]
	s_and_saveexec_b64 s[8:9], vcc
	s_cbranch_execz .LBB0_1323
	s_waitcnt lgkmcnt(0)
	v_add_f32_e32 v86, v86, v87
	ds_write_b32 v126, v86 offset:128

.LBB0_1325:
	s_or_b64 exec, exec, s[8:9]
	v_add_u32_e32 v70, s1, v127
	v_lshl_add_u32 v70, v70, 6, v128
	s_nop 2
	ds_write2_b32 v70, v66, v67 offset1:16
	ds_write2_b32 v70, v68, v69 offset0:32 offset1:48
	v_add_u32_e32 v66, 0x80, v184
	v_ashrrev_i32_e32 v67, 31, v66
	v_lshlrev_b64 v[66:67], 12, v[66:67]
	v_lshl_add_u64 v[66:67], v[186:187], 0, v[66:67]
	global_load_dwordx4 v[82:85], v[66:67], off offset:16 nt
	global_load_dwordx4 v[86:89], v[66:67], off nt
	global_load_dwordx4 v[90:93], v[66:67], off offset:528 nt
	global_load_dwordx4 v[94:97], v[66:67], off offset:512 nt
	v_add_u32_e32 v66, 0x90, v184
	v_ashrrev_i32_e32 v67, 31, v66
	v_lshlrev_b64 v[66:67], 12, v[66:67]
	s_waitcnt lgkmcnt(2)
	v_lshl_add_u64 v[70:71], v[186:187], 0, v[66:67]
	global_load_dwordx4 v[74:77], v[70:71], off offset:16 nt
	global_load_dwordx4 v[78:81], v[70:71], off nt
	global_load_dwordx4 v[66:69], v[70:71], off offset:528 nt
	s_nop 0
	global_load_dwordx4 v[70:73], v[70:71], off offset:512 nt
	s_add_i32 s1, s5, 0x80
	s_waitcnt vmcnt(6)
	v_pk_fma_f32 v[86:87], v[62:63], v[142:143], v[86:87]
	v_pk_fma_f32 v[64:65], v[64:65], v[144:145], v[88:89]
	v_cvt_pk_bf16_f32 v62, v86, v87
	v_lshlrev_b32_e32 v88, 16, v62
	v_and_b32_e32 v89, 0xffff0000, v62
	v_cvt_pk_bf16_f32 v63, v64, v65
	v_pk_mul_f32 v[102:103], v[86:87], v[86:87]
	v_pk_add_f32 v[86:87], v[86:87], v[88:89] neg_lo:[0,1] neg_hi:[0,1]
	v_lshlrev_b32_e32 v88, 16, v63
	v_and_b32_e32 v89, 0xffff0000, v63
	v_pk_mul_f32 v[100:101], v[64:65], v[64:65]
	v_pk_add_f32 v[64:65], v[64:65], v[88:89] neg_lo:[0,1] neg_hi:[0,1]
	v_pk_fma_f32 v[84:85], v[60:61], v[140:141], v[84:85]
	v_pk_fma_f32 v[58:59], v[58:59], v[138:139], v[82:83]
	v_cvt_pk_bf16_f32 v86, v86, v87
	v_cvt_pk_bf16_f32 v87, v64, v65
	v_cvt_pk_bf16_f32 v64, v58, v59
	v_cvt_pk_bf16_f32 v65, v84, v85
	v_lshlrev_b32_e32 v60, 16, v64
	v_and_b32_e32 v61, 0xffff0000, v64
	v_pk_mul_f32 v[104:105], v[58:59], v[58:59]
	v_pk_add_f32 v[58:59], v[58:59], v[60:61] neg_lo:[0,1] neg_hi:[0,1]
	v_add_u32_e32 v98, s1, v189
	v_cvt_pk_bf16_f32 v88, v58, v59
	v_mfma_f32_16x16x32_bf16 v[58:61], v[62:65], v[146:149], 0
	v_ashrrev_i32_e32 v99, 31, v98
	v_lshlrev_b32_e32 v106, 16, v65
	v_and_b32_e32 v107, 0xffff0000, v65
	v_lshlrev_b64 v[98:99], 11, v[98:99]
	v_pk_mul_f32 v[82:83], v[84:85], v[84:85]
	v_pk_add_f32 v[84:85], v[84:85], v[106:107] neg_lo:[0,1] neg_hi:[0,1]
	v_mfma_f32_16x16x32_bf16 v[58:61], v[62:65], v[154:157], v[58:61]
	v_cvt_pk_bf16_f32 v89, v84, v85
	v_lshl_add_u64 v[84:85], s[6:7], 0, v[98:99]
	v_lshl_add_u64 v[84:85], v[182:183], 1, v[84:85]
	global_store_dwordx4 v[84:85], v[62:65], off
	s_waitcnt vmcnt(5)
	v_pk_fma_f32 v[56:57], v[56:57], v[124:125], v[96:97]
	v_mfma_f32_16x16x32_bf16 v[58:61], v[86:89], v[146:149], v[58:61]
	v_fma_f32 v62, v54, v122, v94
	v_fma_f32 v63, v55, v123, v95
	v_cvt_pk_bf16_f32 v55, v56, v57
	v_cvt_pk_bf16_f32 v54, v62, v63
	v_lshlrev_b32_e32 v64, 16, v54
	v_and_b32_e32 v65, 0xffff0000, v54
	v_pk_mul_f32 v[88:89], v[62:63], v[62:63]
	v_pk_add_f32 v[62:63], v[62:63], v[64:65] neg_lo:[0,1] neg_hi:[0,1]
	v_lshlrev_b32_e32 v64, 16, v55
	v_and_b32_e32 v65, 0xffff0000, v55
	v_pk_mul_f32 v[86:87], v[56:57], v[56:57]
	v_pk_add_f32 v[56:57], v[56:57], v[64:65] neg_lo:[0,1] neg_hi:[0,1]
	v_pk_fma_f32 v[50:51], v[50:51], v[114:115], v[90:91]
	v_cvt_pk_bf16_f32 v62, v62, v63
	v_cvt_pk_bf16_f32 v63, v56, v57
	v_cvt_pk_bf16_f32 v56, v50, v51
	v_pk_fma_f32 v[92:93], v[52:53], v[116:117], v[92:93]
	v_lshlrev_b32_e32 v64, 16, v56
	v_and_b32_e32 v65, 0xffff0000, v56
	v_pk_mul_f32 v[52:53], v[92:93], v[92:93]
	v_pk_mul_f32 v[90:91], v[50:51], v[50:51]
	v_pk_add_f32 v[50:51], v[50:51], v[64:65] neg_lo:[0,1] neg_hi:[0,1]
	v_cvt_pk_bf16_f32 v57, v92, v93
	v_cvt_pk_bf16_f32 v64, v50, v51
	v_add_f32_e32 v50, v52, v53
	v_add_f32_e32 v51, v90, v91
	v_add_f32_e32 v50, v51, v50
	v_add_f32_e32 v51, v86, v87
	v_add_f32_e32 v52, v88, v89
	v_add_f32_e32 v51, v52, v51
	v_add_f32_e32 v50, v51, v50
	v_add_f32_e32 v51, v82, v83
	v_add_f32_e32 v52, v104, v105
	v_add_f32_e32 v51, v52, v51
	v_add_f32_e32 v52, v100, v101
	v_add_f32_e32 v53, v102, v103
	v_add_f32_e32 v52, v53, v52
	v_add_f32_e32 v51, v52, v51
	v_add_f32_e32 v82, v51, v50
	v_mfma_f32_16x16x32_bf16 v[50:53], v[54:57], v[130:133], v[58:61]
	v_lshlrev_b32_e32 v94, 16, v57
	v_and_b32_e32 v95, 0xffff0000, v57
	global_store_dwordx4 v[84:85], v[54:57], off offset:256
	ds_bpermute_b32 v60, v188, v82
	v_pk_add_f32 v[58:59], v[92:93], v[94:95] neg_lo:[0,1] neg_hi:[0,1]
	v_mfma_f32_16x16x32_bf16 v[50:53], v[54:57], v[134:137], v[50:53]
	v_cvt_pk_bf16_f32 v65, v58, v59
	s_waitcnt lgkmcnt(0)
	v_add_f32_e32 v54, v82, v60
	ds_bpermute_b32 v55, v185, v54
	v_mfma_f32_16x16x32_bf16 v[50:53], v[62:65], v[130:133], v[50:53]
	s_and_saveexec_b64 s[8:9], vcc
	s_cbranch_execz .LBB0_1327
	s_waitcnt lgkmcnt(0)
	v_add_f32_e32 v54, v54, v55
	ds_write_b32 v126, v54 offset:512

.LBB0_1329:
	s_or_b64 exec, exec, s[8:9]
	v_add_u32_e32 v38, s1, v127
	v_lshl_add_u32 v38, v38, 6, v128
	s_nop 2
	ds_write2_b32 v38, v34, v35 offset1:16
	ds_write2_b32 v38, v36, v37 offset0:32 offset1:48
	v_add_u32_e32 v34, 0xa0, v184
	v_ashrrev_i32_e32 v35, 31, v34
	v_lshlrev_b64 v[34:35], 12, v[34:35]
	v_lshl_add_u64 v[34:35], v[186:187], 0, v[34:35]
	global_load_dwordx4 v[50:53], v[34:35], off offset:16 nt
	global_load_dwordx4 v[54:57], v[34:35], off nt
	global_load_dwordx4 v[58:61], v[34:35], off offset:528 nt
	global_load_dwordx4 v[62:65], v[34:35], off offset:512 nt
	v_add_u32_e32 v34, 0xb0, v184
	v_ashrrev_i32_e32 v35, 31, v34
	v_lshlrev_b64 v[34:35], 12, v[34:35]
	v_lshl_add_u64 v[66:67], v[186:187], 0, v[34:35]
	global_load_dwordx4 v[42:45], v[66:67], off offset:16 nt
	global_load_dwordx4 v[46:49], v[66:67], off nt
	global_load_dwordx4 v[34:37], v[66:67], off offset:528 nt
	s_waitcnt lgkmcnt(2)
	global_load_dwordx4 v[38:41], v[66:67], off offset:512 nt
	s_waitcnt vmcnt(6)
	v_pk_fma_f32 v[54:55], v[30:31], v[142:143], v[54:55]
	v_pk_fma_f32 v[32:33], v[32:33], v[144:145], v[56:57]
	v_cvt_pk_bf16_f32 v30, v54, v55
	v_lshlrev_b32_e32 v56, 16, v30
	v_and_b32_e32 v57, 0xffff0000, v30
	v_cvt_pk_bf16_f32 v31, v32, v33
	v_pk_mul_f32 v[70:71], v[54:55], v[54:55]
	v_pk_add_f32 v[54:55], v[54:55], v[56:57] neg_lo:[0,1] neg_hi:[0,1]
	v_lshlrev_b32_e32 v56, 16, v31
	v_and_b32_e32 v57, 0xffff0000, v31
	v_pk_mul_f32 v[68:69], v[32:33], v[32:33]
	v_pk_add_f32 v[32:33], v[32:33], v[56:57] neg_lo:[0,1] neg_hi:[0,1]
	v_pk_fma_f32 v[52:53], v[28:29], v[140:141], v[52:53]
	v_pk_fma_f32 v[26:27], v[26:27], v[138:139], v[50:51]
	v_cvt_pk_bf16_f32 v54, v54, v55
	v_cvt_pk_bf16_f32 v55, v32, v33
	v_cvt_pk_bf16_f32 v32, v26, v27
	v_cvt_pk_bf16_f32 v33, v52, v53
	v_lshlrev_b32_e32 v28, 16, v32
	v_and_b32_e32 v29, 0xffff0000, v32
	s_add_i32 s1, s5, 0xa0
	v_pk_mul_f32 v[72:73], v[26:27], v[26:27]
	v_pk_add_f32 v[26:27], v[26:27], v[28:29] neg_lo:[0,1] neg_hi:[0,1]
	v_add_u32_e32 v66, s1, v189
	v_cvt_pk_bf16_f32 v56, v26, v27
	v_mfma_f32_16x16x32_bf16 v[26:29], v[30:33], v[146:149], 0
	v_ashrrev_i32_e32 v67, 31, v66
	v_lshlrev_b32_e32 v74, 16, v33
	v_and_b32_e32 v75, 0xffff0000, v33
	v_lshlrev_b64 v[66:67], 11, v[66:67]
	v_pk_mul_f32 v[50:51], v[52:53], v[52:53]
	v_pk_add_f32 v[52:53], v[52:53], v[74:75] neg_lo:[0,1] neg_hi:[0,1]
	v_mfma_f32_16x16x32_bf16 v[26:29], v[30:33], v[154:157], v[26:29]
	v_cvt_pk_bf16_f32 v57, v52, v53
	v_lshl_add_u64 v[52:53], s[6:7], 0, v[66:67]
	v_lshl_add_u64 v[52:53], v[182:183], 1, v[52:53]
	global_store_dwordx4 v[52:53], v[30:33], off
	s_waitcnt vmcnt(5)
	v_pk_fma_f32 v[24:25], v[24:25], v[124:125], v[64:65]
	v_mfma_f32_16x16x32_bf16 v[26:29], v[54:57], v[146:149], v[26:29]
	v_fma_f32 v30, v22, v122, v62
	v_fma_f32 v31, v23, v123, v63
	v_cvt_pk_bf16_f32 v23, v24, v25
	v_cvt_pk_bf16_f32 v22, v30, v31
	v_lshlrev_b32_e32 v32, 16, v22
	v_and_b32_e32 v33, 0xffff0000, v22
	v_pk_mul_f32 v[56:57], v[30:31], v[30:31]
	v_pk_add_f32 v[30:31], v[30:31], v[32:33] neg_lo:[0,1] neg_hi:[0,1]
	v_lshlrev_b32_e32 v32, 16, v23
	v_and_b32_e32 v33, 0xffff0000, v23
	v_pk_mul_f32 v[54:55], v[24:25], v[24:25]
	v_pk_add_f32 v[24:25], v[24:25], v[32:33] neg_lo:[0,1] neg_hi:[0,1]
	v_pk_fma_f32 v[18:19], v[18:19], v[114:115], v[58:59]
	v_cvt_pk_bf16_f32 v30, v30, v31
	v_cvt_pk_bf16_f32 v31, v24, v25
	v_cvt_pk_bf16_f32 v24, v18, v19
	v_pk_fma_f32 v[60:61], v[20:21], v[116:117], v[60:61]
	v_lshlrev_b32_e32 v32, 16, v24
	v_and_b32_e32 v33, 0xffff0000, v24
	v_pk_mul_f32 v[20:21], v[60:61], v[60:61]
	v_pk_mul_f32 v[58:59], v[18:19], v[18:19]
	v_pk_add_f32 v[18:19], v[18:19], v[32:33] neg_lo:[0,1] neg_hi:[0,1]
	v_cvt_pk_bf16_f32 v25, v60, v61
	v_cvt_pk_bf16_f32 v32, v18, v19
	v_add_f32_e32 v18, v20, v21
	v_add_f32_e32 v19, v58, v59
	v_add_f32_e32 v18, v19, v18
	v_add_f32_e32 v19, v54, v55
	v_add_f32_e32 v20, v56, v57
	v_add_f32_e32 v19, v20, v19
	v_add_f32_e32 v18, v19, v18
	v_add_f32_e32 v19, v50, v51
	v_add_f32_e32 v20, v72, v73
	v_add_f32_e32 v19, v20, v19
	v_add_f32_e32 v20, v68, v69
	v_add_f32_e32 v21, v70, v71
	v_add_f32_e32 v20, v21, v20
	v_add_f32_e32 v19, v20, v19
	v_add_f32_e32 v50, v19, v18
	v_mfma_f32_16x16x32_bf16 v[18:21], v[22:25], v[130:133], v[26:29]
	v_lshlrev_b32_e32 v62, 16, v25
	v_and_b32_e32 v63, 0xffff0000, v25
	global_store_dwordx4 v[52:53], v[22:25], off offset:256
	ds_bpermute_b32 v28, v188, v50
	v_pk_add_f32 v[26:27], v[60:61], v[62:63] neg_lo:[0,1] neg_hi:[0,1]
	v_mfma_f32_16x16x32_bf16 v[18:21], v[22:25], v[134:137], v[18:21]
	v_cvt_pk_bf16_f32 v33, v26, v27
	s_waitcnt lgkmcnt(0)
	v_add_f32_e32 v22, v50, v28
	ds_bpermute_b32 v23, v185, v22
	v_mfma_f32_16x16x32_bf16 v[18:21], v[30:33], v[130:133], v[18:21]
	s_and_saveexec_b64 s[8:9], vcc
	s_cbranch_execz .LBB0_1331
	s_waitcnt lgkmcnt(0)
	v_add_f32_e32 v22, v22, v23
	ds_write_b32 v126, v22 offset:640
